# P0b gate/up weight conversion: the 8 per-row norm-scale loads hoisted above the tile loads (4 serialized load-wait round trips per item removed), counted vmcnt ladder
# speedup vs baseline: 1.0071x; 1.0071x over previous
; #define LAS __attribute__((address_space(3)))
; __device__ __forceinline__ void transpose_item(const float* W, int ldw, int K, bf16_t* WT, int n_dst0, int src_col0, const float* kscale, LAS float* scr, int kb, int nb, int lane) {
;     ...
;     for (int i = 0; i < 8; ++i) v[i] = __builtin_nontemporal_load((const f32x4*)(W + (size_t)(k0 + 8 * i + r8) * ldw + src_col0 + n0 + 4 * n4));
; #pragma unroll
;     for (int i = 0; i < 8; ++i) { const int kk = 8 * i + r8; f32x4 x = v[i]; if (kscale) x = x * kscale[k0 + kk];
;         LAS float* d = scr + kk * 33 + 4 * n4; d[0] = x.x; d[1] = x.y; d[2] = x.z; d[3] = x.w; }
.LBB0_957:
	v_ashrrev_i32_e32 v0, 31, v66
	v_lshrrev_b32_e32 v0, 25, v0
	v_add_u32_e32 v0, v66, v0
	v_and_b32_e32 v1, 0xff80, v0
	v_sub_u32_e32 v3, v66, v1
	v_lshrrev_b16_sdwa v4, v61, sext(v3) dst_sel:DWORD dst_unused:UNUSED_PAD src0_sel:DWORD src1_sel:BYTE_0
	v_and_b32_e32 v4, 3, v4
	v_add_u16_e32 v4, v3, v4
	v_ashrrev_i32_e32 v67, 8, v0
	v_bfe_u32 v68, v0, 7, 1
	v_ashrrev_i16_sdwa v5, v62, sext(v4) dst_sel:DWORD dst_unused:UNUSED_PAD src0_sel:DWORD src1_sel:BYTE_0
	v_and_b32_e32 v4, 0xfc, v4
	v_cmp_eq_u32_e32 vcc, 0, v68
	v_lshlrev_b32_e32 v2, 7, v67
	v_sub_u16_e32 v3, v3, v4
	v_cndmask_b32_e32 v1, v57, v58, vcc
	v_cndmask_b32_e32 v0, v59, v60, vcc
	v_lshlrev_b32_sdwa v42, v63, sext(v5) dst_sel:DWORD dst_unused:UNUSED_PAD src0_sel:DWORD src1_sel:WORD_0
	v_lshlrev_b32_sdwa v44, v64, sext(v3) dst_sel:DWORD dst_unused:UNUSED_PAD src0_sel:DWORD src1_sel:BYTE_0
	v_ashrrev_i32_e32 v3, 31, v2
	v_or_b32_e32 v32, v42, v36
	v_lshl_add_u64 v[0:1], v[2:3], 2, v[0:1]
	v_ashrrev_i32_e32 v45, 31, v44
	v_lshl_add_u64 v[0:1], v[44:45], 2, v[0:1]
	v_mul_i32_i24_e32 v4, 0x1600, v32
	v_lshl_add_u64 v[0:1], v[0:1], 0, v[38:39]
	v_mul_hi_i32_i24_e32 v3, 0x5800, v32
	v_mul_i32_i24_e32 v2, 0x5800, v32
	v_ashrrev_i32_e32 v5, 31, v4
	v_lshl_add_u64 v[2:3], v[0:1], 0, v[2:3]
	v_lshl_add_u64 v[0:1], v[4:5], 2, v[0:1]
	v_add_co_u32_e32 v4, vcc, s17, v0
	v_ashrrev_i32_e32 v43, 31, v42
	s_nop 0
	v_addc_co_u32_e32 v5, vcc, 0, v1, vcc
	s_and_b64 vcc, exec, s[0:1]
	s_cbranch_vccnz .Lp0b_ks_skip
	v_or_b32_e32 v96, v42, v36
	v_ashrrev_i32_e32 v97, 31, v96
	v_lshl_add_u64 v[96:97], v[96:97], 2, s[74:75]
	v_ashrrev_i32_e32 v99, 31, v42
	v_mov_b32_e32 v98, v42
	v_lshl_add_u64 v[98:99], v[98:99], 0, v[36:37]
	v_lshl_add_u64 v[98:99], v[98:99], 2, s[74:75]
	global_load_dword v100, v[96:97], off
	global_load_dword v102, v[98:99], off offset:32
	global_load_dword v104, v[98:99], off offset:64
	global_load_dword v106, v[98:99], off offset:96
	global_load_dword v108, v[98:99], off offset:128
	global_load_dword v110, v[98:99], off offset:160
	global_load_dword v112, v[98:99], off offset:192
	global_load_dword v114, v[98:99], off offset:224
.Lp0b_ks_skip:
	global_load_dwordx4 v[24:27], v[2:3], off nt
	global_load_dwordx4 v[28:31], v[4:5], off nt
	v_add_co_u32_e32 v2, vcc, s18, v0
	s_nop 1
	v_addc_co_u32_e32 v3, vcc, 0, v1, vcc
	v_add_co_u32_e32 v4, vcc, s19, v0
	s_nop 1
	v_addc_co_u32_e32 v5, vcc, 0, v1, vcc
	global_load_dwordx4 v[16:19], v[2:3], off nt
	global_load_dwordx4 v[20:23], v[4:5], off nt
	v_add_co_u32_e32 v2, vcc, s21, v0
	s_nop 1
	v_addc_co_u32_e32 v3, vcc, 0, v1, vcc
	v_add_co_u32_e32 v4, vcc, 0xdc000, v0
	s_nop 1
	v_addc_co_u32_e32 v5, vcc, 0, v1, vcc
	v_add_co_u32_e32 v34, vcc, 0x108000, v0
	global_load_dwordx4 v[8:11], v[2:3], off nt
	global_load_dwordx4 v[12:15], v[4:5], off nt
	v_addc_co_u32_e32 v35, vcc, 0, v1, vcc
	v_add_co_u32_e32 v46, vcc, 0x134000, v0
	s_nop 1
	v_addc_co_u32_e32 v47, vcc, 0, v1, vcc
	global_load_dwordx4 v[0:3], v[34:35], off nt
	global_load_dwordx4 v[4:7], v[46:47], off nt
	s_and_b64 vcc, exec, s[0:1]
	s_cbranch_vccnz .LBB0_968
	s_waitcnt vmcnt(6)
	v_pk_mul_f32 v[46:47], v[26:27], v[100:101] op_sel_hi:[1,0]
	v_pk_mul_f32 v[48:49], v[24:25], v[100:101] op_sel_hi:[1,0]
	v_pk_mul_f32 v[34:35], v[30:31], v[102:103] op_sel_hi:[1,0]
	v_pk_mul_f32 v[32:33], v[28:29], v[102:103] op_sel_hi:[1,0]
	s_cbranch_execnz .LBB0_960

; #define LAS __attribute__((address_space(3)))
; __device__ __forceinline__ void transpose_item(const float* W, int ldw, int K, bf16_t* WT, int n_dst0, int src_col0, const float* kscale, LAS float* scr, int kb, int nb, int lane) {
;     ...
;     for (int i = 0; i < 8; ++i) { const int kk = 8 * i + r8; f32x4 x = v[i]; if (kscale) x = x * kscale[k0 + kk];
;         LAS float* d = scr + kk * 33 + 4 * n4; d[0] = x.x; d[1] = x.y; d[2] = x.z; d[3] = x.w; }
.LBB0_960:
	s_waitcnt vmcnt(7)
	v_add_u32_e32 v24, 0x420, v65
	ds_write2_b32 v65, v48, v49 offset1:1
	ds_write2_b32 v65, v46, v47 offset0:2 offset1:3
	ds_write2_b32 v24, v32, v33 offset1:1
	v_add_u32_e32 v24, 0x428, v65
	s_and_b64 vcc, exec, s[0:1]
	ds_write2_b32 v24, v34, v35 offset1:1
	s_cbranch_vccnz .LBB0_969
	s_waitcnt vmcnt(4)
	v_pk_mul_f32 v[28:29], v[18:19], v[104:105] op_sel_hi:[1,0]
	v_pk_mul_f32 v[30:31], v[16:17], v[104:105] op_sel_hi:[1,0]
	v_pk_mul_f32 v[26:27], v[22:23], v[106:107] op_sel_hi:[1,0]
	v_pk_mul_f32 v[24:25], v[20:21], v[106:107] op_sel_hi:[1,0]
	s_cbranch_execnz .LBB0_963

; #define LAS __attribute__((address_space(3)))
; __device__ __forceinline__ void transpose_item(const float* W, int ldw, int K, bf16_t* WT, int n_dst0, int src_col0, const float* kscale, LAS float* scr, int kb, int nb, int lane) {
;     ...
;     for (int i = 0; i < 8; ++i) { const int kk = 8 * i + r8; f32x4 x = v[i]; if (kscale) x = x * kscale[k0 + kk];
;         LAS float* d = scr + kk * 33 + 4 * n4; d[0] = x.x; d[1] = x.y; d[2] = x.z; d[3] = x.w; }
.LBB0_963:
	s_waitcnt vmcnt(5)
	v_add_u32_e32 v16, 0x840, v65
	ds_write2_b32 v16, v30, v31 offset1:1
	v_add_u32_e32 v16, 0x848, v65
	ds_write2_b32 v16, v28, v29 offset1:1
	v_add_u32_e32 v16, 0xc60, v65
	ds_write2_b32 v16, v24, v25 offset1:1
	v_add_u32_e32 v16, 0xc68, v65
	s_and_b64 vcc, exec, s[0:1]
	ds_write2_b32 v16, v26, v27 offset1:1
	s_cbranch_vccnz .LBB0_970
	s_waitcnt vmcnt(2)
	v_pk_mul_f32 v[20:21], v[10:11], v[108:109] op_sel_hi:[1,0]
	v_pk_mul_f32 v[22:23], v[8:9], v[108:109] op_sel_hi:[1,0]
	v_pk_mul_f32 v[18:19], v[14:15], v[110:111] op_sel_hi:[1,0]
	v_pk_mul_f32 v[16:17], v[12:13], v[110:111] op_sel_hi:[1,0]
	s_cbranch_execnz .LBB0_966

; #define LAS __attribute__((address_space(3)))
; __device__ __forceinline__ void transpose_item(const float* W, int ldw, int K, bf16_t* WT, int n_dst0, int src_col0, const float* kscale, LAS float* scr, int kb, int nb, int lane) {
;     ...
;     for (int i = 0; i < 8; ++i) { const int kk = 8 * i + r8; f32x4 x = v[i]; if (kscale) x = x * kscale[k0 + kk];
;         LAS float* d = scr + kk * 33 + 4 * n4; d[0] = x.x; d[1] = x.y; d[2] = x.z; d[3] = x.w; }
.LBB0_966:
	s_waitcnt vmcnt(3)
	v_add_u32_e32 v8, 0x1080, v65
	ds_write2_b32 v8, v22, v23 offset1:1
	v_add_u32_e32 v8, 0x1088, v65
	ds_write2_b32 v8, v20, v21 offset1:1
	v_add_u32_e32 v8, 0x14a0, v65
	ds_write2_b32 v8, v16, v17 offset1:1
	v_add_u32_e32 v8, 0x14a8, v65
	s_and_b64 vcc, exec, s[0:1]
	ds_write2_b32 v8, v18, v19 offset1:1
	s_cbranch_vccnz .LBB0_971
	s_waitcnt vmcnt(0)
	v_pk_mul_f32 v[12:13], v[2:3], v[112:113] op_sel_hi:[1,0]
	v_pk_mul_f32 v[14:15], v[0:1], v[112:113] op_sel_hi:[1,0]
	v_pk_mul_f32 v[10:11], v[6:7], v[114:115] op_sel_hi:[1,0]
	v_pk_mul_f32 v[8:9], v[4:5], v[114:115] op_sel_hi:[1,0]
	s_cbranch_execnz .LBB0_956
	s_branch .LBB0_972
